# stack on v018: small-GEMM epilogue ssq load issued early, retout cross-term fragment reads through a 4-deep ring, retout gate loads issued at the tail top
# speedup vs baseline: 1.0390x; 1.0013x over previous
.LBB0_372:
	s_barrier
	ds_write_b128 v184, v[64:67]
	ds_write_b128 v184, v[68:71] offset:64
	ds_write_b128 v184, v[72:75] offset:128
	ds_write_b128 v184, v[76:79] offset:192
	ds_write_b128 v184, v[80:83] offset:4352
	ds_write_b128 v184, v[84:87] offset:4416
	ds_write_b128 v184, v[88:91] offset:4480
	ds_write_b128 v184, v[92:95] offset:4544
	ds_write_b128 v184, v[96:99] offset:8704
	ds_write_b128 v184, v[100:103] offset:8768
	ds_write_b128 v184, v[104:107] offset:8832
	ds_write_b128 v184, v[108:111] offset:8896
	ds_write_b128 v184, v[112:115] offset:13056
	ds_write_b128 v184, v[116:119] offset:13120
	ds_write_b128 v184, v[120:123] offset:13184
	ds_write_b128 v184, v[124:127] offset:13248
	s_waitcnt lgkmcnt(0)
	s_barrier
	s_waitcnt vmcnt(5)
	ds_read_b128 v[8:11], v187
	v_add_u32_e32 v0, s14, v178
	v_cmp_gt_i32_e32 vcc, s73, v0
	v_and_b32_e32 v2, 0x7ff, v0
	v_ashrrev_i32_e32 v1, 31, v0
	v_lshl_add_u64 v[64:65], v[0:1], 2, s[96:97]
	global_load_dword v66, v[64:65], off
	v_cndmask_b32_e32 v2, v180, v2, vcc
	v_lshlrev_b32_e32 v208, 9, v2
	s_waitcnt lgkmcnt(0)
	v_pk_add_f32 v[2:3], v[10:11], 0 op_sel_hi:[1,0]
	s_waitcnt vmcnt(4)
	v_pk_add_f32 v[12:13], v[8:9], 0 op_sel_hi:[1,0]
	ds_read_b128 v[8:11], v187 offset:128
	v_lshlrev_b64 v[6:7], 10, v[0:1]
	s_ashr_i32 s25, s18, 2
	s_cmp_gt_i32 s25, 3
	s_cselect_b64 s[16:17], -1, 0
	s_waitcnt lgkmcnt(0)
	v_pk_add_f32 v[14:15], v[10:11], 0 op_sel_hi:[1,0]
	v_pk_add_f32 v[16:17], v[8:9], 0 op_sel_hi:[1,0]
	ds_read_b128 v[8:11], v187 offset:17408
	s_cmp_gt_u32 s25, 7
	s_cselect_b64 s[14:15], -1, 0
	s_cmp_gt_u32 s25, 9
	s_cselect_b64 s[10:11], -1, 0
	s_waitcnt lgkmcnt(0)
	v_pk_add_f32 v[2:3], v[2:3], v[10:11]
	v_pk_add_f32 v[12:13], v[12:13], v[8:9]
	ds_read_b128 v[8:11], v187 offset:17536
	s_lshl_b32 s6, s25, 1
	s_lshl_b32 s23, s25, 8
	s_and_b32 s6, s6, 2
	s_lshr_b32 s7, s21, 6
	s_waitcnt lgkmcnt(0)
	v_pk_add_f32 v[14:15], v[14:15], v[10:11]
	v_pk_add_f32 v[16:17], v[16:17], v[8:9]
	ds_read_b128 v[8:11], v187 offset:34816
	s_add_i32 s24, s23, 0xfffff600
	s_or_b32 s19, s6, s7
	s_and_b32 s6, s18, 24
	s_cmp_eq_u32 s6, 16
	s_waitcnt lgkmcnt(0)
	v_pk_add_f32 v[2:3], v[2:3], v[10:11]
	v_pk_add_f32 v[12:13], v[12:13], v[8:9]
	ds_read_b128 v[8:11], v187 offset:34944
	s_cselect_b64 s[6:7], -1, 0
	v_cndmask_b32_e64 v4, v232, 1.0, s[6:7]
	s_lshl_b32 s22, s19, 7
	v_or_b32_e32 v5, s21, v179
	s_waitcnt lgkmcnt(0)
	v_pk_add_f32 v[14:15], v[14:15], v[10:11]
	v_pk_add_f32 v[16:17], v[16:17], v[8:9]
	ds_read_b128 v[8:11], v188
	s_mov_b64 s[18:19], -1
	s_waitcnt lgkmcnt(0)
	v_pk_add_f32 v[2:3], v[2:3], v[10:11]
	v_pk_add_f32 v[18:19], v[12:13], v[8:9]
	ds_read_b128 v[8:11], v188 offset:128
	s_waitcnt vmcnt(3) lgkmcnt(0)
	v_pk_add_f32 v[20:21], v[16:17], v[8:9]
	v_lshl_add_u64 v[8:9], v[0:1], 2, s[96:97]
	v_pk_add_f32 v[10:11], v[14:15], v[10:11]
	s_waitcnt vmcnt(0)
	v_fmamk_f32 v0, v66, 0x3a800000, v228
	v_cmp_gt_f32_e32 vcc, s69, v0
	v_mul_f32_e32 v1, 0x4b800000, v0
	s_nop 0
	v_cndmask_b32_e32 v0, v0, v1, vcc
	v_rsq_f32_e32 v0, v0
	s_nop 0
	v_mul_f32_e32 v1, 0x45800000, v0
	v_cndmask_b32_e32 v0, v0, v1, vcc
	v_pk_mul_f32 v[12:13], v[2:3], v[0:1] op_sel_hi:[1,0]
	v_pk_mul_f32 v[14:15], v[18:19], v[0:1] op_sel_hi:[1,0]
	v_pk_mul_f32 v[16:17], v[10:11], v[0:1] op_sel_hi:[1,0]
	v_pk_mul_f32 v[18:19], v[20:21], v[0:1] op_sel_hi:[1,0]
	s_and_b64 vcc, exec, s[16:17]
	s_cbranch_vccz .LBB0_382
	s_and_b64 vcc, exec, s[14:15]
	s_cbranch_vccz .LBB0_379
	s_and_b64 vcc, exec, s[10:11]
	s_cbranch_vccz .LBB0_376
	v_or_b32_e32 v10, s24, v5
	v_mov_b32_e32 v11, v209
	v_lshl_add_u64 v[0:1], v[10:11], 2, s[12:13]
	global_load_dwordx4 v[20:23], v[0:1], off
	s_nop 0
	global_load_dwordx4 v[0:3], v[0:1], off offset:512
	v_lshl_add_u64 v[24:25], s[54:55], 0, v[6:7]
	v_lshl_add_u64 v[10:11], v[10:11], 1, v[24:25]
	v_mul_f32_e32 v24, 0xbfb8aa3b, v14
	v_mul_f32_e32 v25, 0xbfb8aa3b, v15
	v_exp_f32_e32 v24, v24
	v_exp_f32_e32 v25, v25
	s_mov_b64 s[18:19], 0
	v_add_f32_e32 v24, 1.0, v24
	v_add_f32_e32 v25, 1.0, v25
	v_rcp_f32_e32 v24, v24
	v_rcp_f32_e32 v25, v25
	s_nop 0
	v_pk_mul_f32 v[24:25], v[14:15], v[24:25]
	s_waitcnt vmcnt(1)
	v_pk_mul_f32 v[20:21], v[24:25], v[20:21]
	s_nop 0
	v_cvt_pk_bf16_f32 v20, v20, v21
	v_mul_f32_e32 v21, 0xbfb8aa3b, v12
	v_exp_f32_e32 v21, v21
	s_nop 0
	v_add_f32_e32 v21, 1.0, v21
	v_rcp_f32_e32 v24, v21
	v_mul_f32_e32 v21, 0xbfb8aa3b, v13
	v_exp_f32_e32 v21, v21
	s_nop 0
	v_add_f32_e32 v21, 1.0, v21
	v_rcp_f32_e32 v25, v21
	s_nop 0
	v_pk_mul_f32 v[24:25], v[12:13], v[24:25]
	s_nop 0
	v_pk_mul_f32 v[22:23], v[24:25], v[22:23]
	s_nop 0
	v_cvt_pk_bf16_f32 v21, v22, v23
	v_mul_f32_e32 v22, 0xbfb8aa3b, v18
	v_mul_f32_e32 v23, 0xbfb8aa3b, v19
	v_exp_f32_e32 v22, v22
	v_exp_f32_e32 v23, v23
	v_add_f32_e32 v22, 1.0, v22
	v_add_f32_e32 v23, 1.0, v23
	v_rcp_f32_e32 v22, v22
	v_rcp_f32_e32 v23, v23
	s_nop 0
	v_pk_mul_f32 v[22:23], v[18:19], v[22:23]
	s_waitcnt vmcnt(0)
	v_pk_mul_f32 v[0:1], v[22:23], v[0:1]
	s_nop 0
	v_cvt_pk_bf16_f32 v0, v0, v1
	v_mul_f32_e32 v1, 0xbfb8aa3b, v16
	v_exp_f32_e32 v1, v1
	s_nop 0
	v_add_f32_e32 v1, 1.0, v1
	v_rcp_f32_e32 v22, v1
	v_mul_f32_e32 v1, 0xbfb8aa3b, v17
	v_exp_f32_e32 v1, v1
	s_nop 0
	v_add_f32_e32 v1, 1.0, v1
	v_rcp_f32_e32 v23, v1
	s_nop 0
	v_pk_mul_f32 v[22:23], v[16:17], v[22:23]
	s_nop 0
	v_pk_mul_f32 v[2:3], v[22:23], v[2:3]
	s_nop 0
	v_cvt_pk_bf16_f32 v1, v2, v3
	global_store_dwordx2 v[10:11], v[20:21], off
	global_store_dwordx2 v[10:11], v[0:1], off offset:256

.LBB0_627:
	v_add3_u32 v64, v236, s17, 1
	v_cvt_f32_i32_e32 v64, v64
	s_lshl_b32 s92, s0, 1
	v_lshl_add_u64 v[100:101], s[54:55], 0, v[224:225]
	v_lshl_add_u64 v[100:101], v[100:101], 0, s[92:93]
	v_lshlrev_b64 v[118:119], 1, v[208:209]
	v_lshl_add_u64 v[100:101], v[100:101], 0, v[118:119]
	global_load_dwordx2 v[102:103], v[100:101], off
	global_load_dwordx2 v[104:105], v[100:101], off offset:32
	global_load_dwordx2 v[106:107], v[100:101], off offset:64
	global_load_dwordx2 v[108:109], v[100:101], off offset:96
	global_load_dwordx2 v[110:111], v[100:101], off offset:128
	global_load_dwordx2 v[112:113], v[100:101], off offset:160
	global_load_dwordx2 v[114:115], v[100:101], off offset:192
	global_load_dwordx2 v[116:117], v[100:101], off offset:224
	s_add_i32 s16, s16, s78
	s_cmpk_gt_i32 s16, 0x1ff
	v_mul_f32_e32 v65, v235, v64
	v_cmp_gt_f32_e32 vcc, s3, v65
	s_nop 1
	v_cndmask_b32_e32 v65, 0, v233, vcc
	v_fmac_f32_e32 v65, v235, v64
	v_exp_f32_e32 v64, v65
	v_cndmask_b32_e32 v65, 0, v234, vcc
	v_ldexp_f32 v64, v64, v65
	v_pk_fma_f32 v[28:29], v[64:65], v[56:57], v[28:29] op_sel_hi:[0,1,1]
	v_pk_fma_f32 v[24:25], v[64:65], v[60:61], v[24:25] op_sel_hi:[0,1,1]
	v_pk_fma_f32 v[30:31], v[64:65], v[58:59], v[30:31] op_sel_hi:[0,1,1]
	v_pk_fma_f32 v[26:27], v[64:65], v[62:63], v[26:27] op_sel_hi:[0,1,1]
	v_mov_b32_e32 v56, v24
	v_mov_b32_e32 v57, v28
	v_mov_b32_e32 v58, v25
	v_mov_b32_e32 v59, v29
	v_pk_add_f32 v[56:57], v[56:57], v[58:59]
	v_mov_b32_e32 v58, v26
	v_mov_b32_e32 v59, v30
	v_mov_b32_e32 v60, v27
	v_mov_b32_e32 v61, v31
	v_pk_fma_f32 v[18:19], v[64:65], v[46:47], v[18:19] op_sel_hi:[0,1,1]
	v_pk_fma_f32 v[16:17], v[64:65], v[44:45], v[16:17] op_sel_hi:[0,1,1]
	v_pk_add_f32 v[58:59], v[58:59], v[60:61]
	v_pk_mov_b32 v[44:45], v[16:17], v[18:19] op_sel:[1,0]
	v_mov_b32_e32 v46, v16
	v_mov_b32_e32 v47, v19
	v_pk_add_f32 v[56:57], v[56:57], v[58:59]
	v_pk_add_f32 v[44:45], v[44:45], v[46:47]
	v_add_f32_e32 v57, 0, v57
	v_pk_add_f32 v[44:45], v[44:45], v[44:45] op_sel_hi:[0,1]
	v_pk_fma_f32 v[14:15], v[64:65], v[42:43], v[14:15] op_sel_hi:[0,1,1]
	v_pk_fma_f32 v[40:41], v[64:65], v[40:41], v[12:13] op_sel_hi:[0,1,1]
	v_pk_fma_f32 v[12:13], v[64:65], v[50:51], v[22:23] op_sel_hi:[0,1,1]
	v_pk_fma_f32 v[20:21], v[64:65], v[48:49], v[20:21] op_sel_hi:[0,1,1]
	v_add_f32_e32 v57, v56, v57
	v_add_f32_e32 v43, v40, v41
	v_add_f32_e32 v47, v14, v15
	v_mov_b32_e32 v42, v20
	v_mov_b32_e32 v46, v21
	v_mov_b32_e32 v44, v12
	v_mov_b32_e32 v56, v13
	v_pk_fma_f32 v[10:11], v[64:65], v[38:39], v[10:11] op_sel_hi:[0,1,1]
	v_pk_fma_f32 v[8:9], v[64:65], v[36:37], v[8:9] op_sel_hi:[0,1,1]
	v_pk_add_f32 v[22:23], v[42:43], v[46:47]
	v_pk_add_f32 v[42:43], v[44:45], v[56:57]
	v_pk_mov_b32 v[36:37], v[8:9], v[10:11] op_sel:[1,0]
	v_mov_b32_e32 v38, v8
	v_mov_b32_e32 v39, v11
	v_pk_add_f32 v[22:23], v[22:23], v[42:43]
	v_pk_add_f32 v[36:37], v[36:37], v[38:39]
	v_pk_add_f32 v[22:23], v[22:23], v[22:23] op_sel_hi:[0,1]
	v_pk_add_f32 v[36:37], v[36:37], v[36:37] op_sel_hi:[0,1]
	v_pk_fma_f32 v[6:7], v[64:65], v[34:35], v[6:7] op_sel_hi:[0,1,1]
	v_pk_fma_f32 v[4:5], v[64:65], v[32:33], v[4:5] op_sel_hi:[0,1,1]
	v_pk_fma_f32 v[2:3], v[64:65], v[54:55], v[2:3] op_sel_hi:[0,1,1]
	v_pk_fma_f32 v[0:1], v[64:65], v[52:53], v[0:1] op_sel_hi:[0,1,1]
	v_add_f32_e32 v33, v4, v5
	v_add_f32_e32 v35, v6, v7
	v_mov_b32_e32 v32, v0
	v_mov_b32_e32 v34, v1
	v_mov_b32_e32 v36, v2
	v_mov_b32_e32 v22, v3
	v_pk_add_f32 v[32:33], v[32:33], v[34:35]
	v_pk_add_f32 v[22:23], v[36:37], v[22:23]
	s_nop 0
	v_pk_add_f32 v[22:23], v[32:33], v[22:23]
	v_and_b32_e32 v32, 64, v230
	v_add_f32_e32 v22, v22, v23
	v_xor_b32_e32 v23, 16, v230
	v_add_u32_e32 v32, 64, v32
	v_cmp_lt_i32_e32 vcc, v23, v32
	s_nop 1
	v_cndmask_b32_e32 v23, v230, v23, vcc
	v_lshlrev_b32_e32 v54, 2, v23
	v_mov_b32_e32 v23, v22
	s_nop 1
	v_permlane16_swap_b32 v23, v22
	s_waitcnt lgkmcnt(0)
	v_add_f32_e32 v22, v22, v23
	v_xor_b32_e32 v23, 32, v230
	v_cmp_lt_i32_e32 vcc, v23, v32
	s_nop 1
	v_cndmask_b32_e32 v23, v230, v23, vcc
	v_lshlrev_b32_e32 v55, 2, v23
	v_mov_b32_e32 v23, v22
	v_mov_b32_e32 v66, v22
	s_nop 1
	v_permlane32_swap_b32 v23, v66
	s_waitcnt lgkmcnt(0)
	v_add_f32_e32 v52, v66, v23
	v_fmamk_f32 v29, v52, 0xbc000000, v29
	v_fmamk_f32 v25, v52, 0xbc000000, v25
	v_fmamk_f32 v31, v52, 0xbc000000, v31
	v_fmac_f32_e32 v28, 0xbc000000, v52
	v_fmamk_f32 v27, v52, 0xbc000000, v27
	v_fmac_f32_e32 v24, 0xbc000000, v52
	v_mov_b32_e32 v32, v29
	v_mov_b32_e32 v33, v25
	v_fmac_f32_e32 v30, 0xbc000000, v52
	v_fmac_f32_e32 v26, 0xbc000000, v52
	v_mov_b32_e32 v22, v28
	v_mov_b32_e32 v23, v24
	v_pk_mul_f32 v[32:33], v[32:33], v[32:33]
	v_mov_b32_e32 v34, v31
	v_mov_b32_e32 v35, v27
	v_pk_fma_f32 v[22:23], v[22:23], v[22:23], v[32:33]
	v_mov_b32_e32 v32, v30
	v_mov_b32_e32 v33, v26
	v_pk_mul_f32 v[34:35], v[34:35], v[34:35]
	v_fmamk_f32 v17, v52, 0xbc000000, v17
	v_pk_fma_f32 v[32:33], v[32:33], v[32:33], v[34:35]
	v_fmac_f32_e32 v16, 0xbc000000, v52
	v_pk_add_f32 v[22:23], v[22:23], v[32:33]
	v_fmamk_f32 v19, v52, 0xbc000000, v19
	v_fmac_f32_e32 v18, 0xbc000000, v52
	v_pk_add_f32 v[22:23], v[22:23], v[22:23] op_sel_hi:[0,1]
	v_pk_mul_f32 v[32:33], v[18:19], v[18:19]
	v_pk_mul_f32 v[34:35], v[16:17], v[16:17]
	v_fmac_f32_e32 v40, 0xbc000000, v52
	v_pk_mov_b32 v[36:37], v[34:35], v[32:33] op_sel:[1,0]
	v_mov_b32_e32 v35, v33
	v_fmac_f32_e32 v14, 0xbc000000, v52
	v_fmamk_f32 v41, v52, 0xbc000000, v41
	v_mul_f32_e32 v22, v40, v40
	v_pk_add_f32 v[32:33], v[36:37], v[34:35]
	v_fmamk_f32 v15, v52, 0xbc000000, v15
	v_lshl_add_u64 v[34:35], s[54:55], 0, v[224:225]
	v_pk_fma_f32 v[42:43], v[40:41], v[40:41], v[22:23] op_sel_hi:[1,1,0]
	v_mul_f32_e32 v22, v14, v14
	v_pk_add_f32 v[32:33], v[32:33], v[32:33] op_sel_hi:[0,1]
	v_lshl_add_u64 v[34:35], v[34:35], 0, s[92:93]
	v_lshlrev_b64 v[36:37], 1, v[208:209]
	v_pk_fma_f32 v[44:45], v[14:15], v[14:15], v[22:23] op_sel_hi:[1,1,0]
	v_fmamk_f32 v13, v52, 0xbc000000, v13
	v_fmac_f32_e32 v12, 0xbc000000, v52
	v_fmamk_f32 v21, v52, 0xbc000000, v21
	v_fmac_f32_e32 v20, 0xbc000000, v52
	v_lshl_add_u64 v[34:35], v[34:35], 0, v[36:37]
	v_mul_f32_e32 v42, v20, v20
	v_mul_f32_e32 v44, v21, v21
	v_mul_f32_e32 v32, v12, v12
	v_mul_f32_e32 v22, v13, v13
	s_waitcnt vmcnt(0)
	v_mov_b32_e32 v38, v102
	v_mov_b32_e32 v39, v103
	v_mov_b32_e32 v46, v104
	v_mov_b32_e32 v47, v105
	v_pk_add_f32 v[42:43], v[42:43], v[44:45]
	v_pk_add_f32 v[22:23], v[32:33], v[22:23]
	v_fmamk_f32 v9, v52, 0xbc000000, v9
	v_pk_add_f32 v[22:23], v[42:43], v[22:23]
	v_fmac_f32_e32 v8, 0xbc000000, v52
	v_fmamk_f32 v11, v52, 0xbc000000, v11
	v_fmac_f32_e32 v10, 0xbc000000, v52
	v_pk_add_f32 v[22:23], v[22:23], v[22:23] op_sel_hi:[0,1]
	v_pk_mul_f32 v[42:43], v[10:11], v[10:11]
	v_pk_mul_f32 v[44:45], v[8:9], v[8:9]
	v_fmac_f32_e32 v4, 0xbc000000, v52
	v_pk_mov_b32 v[48:49], v[44:45], v[42:43] op_sel:[1,0]
	v_mov_b32_e32 v45, v43
	v_fmac_f32_e32 v6, 0xbc000000, v52
	v_fmamk_f32 v5, v52, 0xbc000000, v5
	v_mul_f32_e32 v22, v4, v4
	v_pk_add_f32 v[42:43], v[48:49], v[44:45]
	v_fmamk_f32 v7, v52, 0xbc000000, v7
	v_pk_fma_f32 v[48:49], v[4:5], v[4:5], v[22:23] op_sel_hi:[1,1,0]
	v_mul_f32_e32 v22, v6, v6
	v_pk_add_f32 v[42:43], v[42:43], v[42:43] op_sel_hi:[0,1]
	v_pk_fma_f32 v[50:51], v[6:7], v[6:7], v[22:23] op_sel_hi:[1,1,0]
	v_fmamk_f32 v3, v52, 0xbc000000, v3
	v_fmac_f32_e32 v2, 0xbc000000, v52
	v_fmamk_f32 v1, v52, 0xbc000000, v1
	v_fmac_f32_e32 v0, 0xbc000000, v52
	v_mul_f32_e32 v48, v0, v0
	v_mul_f32_e32 v50, v1, v1
	v_mul_f32_e32 v42, v2, v2
	v_mul_f32_e32 v22, v3, v3
	v_mov_b32_e32 v32, v106
	v_mov_b32_e32 v33, v107
	v_mov_b32_e32 v44, v108
	v_mov_b32_e32 v45, v109
	v_pk_add_f32 v[48:49], v[48:49], v[50:51]
	v_pk_add_f32 v[22:23], v[42:43], v[22:23]
	v_mov_b32_e32 v52, v110
	v_mov_b32_e32 v53, v111
	v_pk_add_f32 v[22:23], v[48:49], v[22:23]
	v_lshlrev_b64 v[50:51], 11, v[222:223]
	v_add_f32_e32 v42, v22, v23
	v_mov_b32_e32 v43, v42
	s_nop 1
	v_permlane16_swap_b32 v43, v42
	v_mov_b32_e32 v22, v112
	v_mov_b32_e32 v23, v113
	v_lshl_add_u64 v[50:51], s[86:87], 0, v[50:51]
	v_lshl_add_u64 v[50:51], v[50:51], 0, s[92:93]
	v_lshl_add_u64 v[36:37], v[50:51], 0, v[36:37]
	s_waitcnt lgkmcnt(0)
	v_add_f32_e32 v42, v42, v43
	v_mov_b32_e32 v43, v42
	s_nop 1
	v_permlane32_swap_b32 v43, v42
	s_waitcnt lgkmcnt(0)
	v_add_f32_e32 v42, v42, v43
	v_fmamk_f32 v48, v42, 0x3c000000, v228
	v_mov_b32_e32 v42, v114
	v_mov_b32_e32 v43, v115
	v_mul_f32_e32 v49, 0x4b800000, v48
	v_mov_b32_e32 v34, v116
	v_mov_b32_e32 v35, v117
	v_cmp_gt_f32_e32 vcc, s69, v48
	s_waitcnt vmcnt(7)
	v_lshlrev_b32_e32 v50, 16, v38
	v_cndmask_b32_e32 v48, v48, v49, vcc
	v_rsq_f32_e32 v48, v48
	v_and_b32_e32 v51, 0xffff0000, v38
	v_lshlrev_b32_e32 v38, 16, v39
	v_and_b32_e32 v39, 0xffff0000, v39
	v_mul_f32_e32 v49, 0x45800000, v48
	v_cndmask_b32_e32 v48, v48, v49, vcc
	v_pk_mul_f32 v[28:29], v[28:29], v[48:49] op_sel_hi:[1,0]
	v_pk_mul_f32 v[30:31], v[30:31], v[48:49] op_sel_hi:[1,0]
	v_pk_mul_f32 v[28:29], v[28:29], v[50:51]
	v_pk_mul_f32 v[30:31], v[30:31], v[38:39]
	v_cvt_pk_bf16_f32 v28, v28, v29
	v_cvt_pk_bf16_f32 v29, v30, v31
	global_store_dwordx2 v[36:37], v[28:29], off offset:1024
	v_pk_mul_f32 v[24:25], v[24:25], v[48:49] op_sel_hi:[1,0]
	s_waitcnt vmcnt(7)
	v_lshlrev_b32_e32 v28, 16, v46
	v_and_b32_e32 v29, 0xffff0000, v46
	v_pk_mul_f32 v[24:25], v[24:25], v[28:29]
	v_pk_mul_f32 v[26:27], v[26:27], v[48:49] op_sel_hi:[1,0]
	v_lshlrev_b32_e32 v28, 16, v47
	v_and_b32_e32 v29, 0xffff0000, v47
	v_pk_mul_f32 v[26:27], v[26:27], v[28:29]
	v_cvt_pk_bf16_f32 v24, v24, v25
	v_cvt_pk_bf16_f32 v25, v26, v27
	global_store_dwordx2 v[36:37], v[24:25], off offset:1056
	v_pk_mul_f32 v[16:17], v[16:17], v[48:49] op_sel_hi:[1,0]
	v_pk_mul_f32 v[18:19], v[18:19], v[48:49] op_sel_hi:[1,0]
	v_pk_mul_f32 v[14:15], v[14:15], v[48:49] op_sel_hi:[1,0]
	v_pk_mul_f32 v[12:13], v[12:13], v[48:49] op_sel_hi:[1,0]
	v_pk_mul_f32 v[8:9], v[8:9], v[48:49] op_sel_hi:[1,0]
	v_pk_mul_f32 v[10:11], v[10:11], v[48:49] op_sel_hi:[1,0]
	s_waitcnt vmcnt(7)
	v_lshlrev_b32_e32 v24, 16, v32
	v_and_b32_e32 v25, 0xffff0000, v32
	v_pk_mul_f32 v[16:17], v[16:17], v[24:25]
	v_lshlrev_b32_e32 v24, 16, v33
	v_and_b32_e32 v25, 0xffff0000, v33
	v_pk_mul_f32 v[18:19], v[18:19], v[24:25]
	v_cvt_pk_bf16_f32 v16, v16, v17
	v_cvt_pk_bf16_f32 v17, v18, v19
	global_store_dwordx2 v[36:37], v[16:17], off offset:1088
	v_pk_mul_f32 v[16:17], v[40:41], v[48:49] op_sel_hi:[1,0]
	s_waitcnt vmcnt(7)
	v_lshlrev_b32_e32 v18, 16, v44
	v_and_b32_e32 v19, 0xffff0000, v44
	v_pk_mul_f32 v[16:17], v[16:17], v[18:19]
	v_lshlrev_b32_e32 v18, 16, v45
	v_and_b32_e32 v19, 0xffff0000, v45
	v_pk_mul_f32 v[14:15], v[14:15], v[18:19]
	v_cvt_pk_bf16_f32 v16, v16, v17
	v_cvt_pk_bf16_f32 v17, v14, v15
	global_store_dwordx2 v[36:37], v[16:17], off offset:1120
	v_pk_mul_f32 v[14:15], v[20:21], v[48:49] op_sel_hi:[1,0]
	s_waitcnt vmcnt(7)
	v_lshlrev_b32_e32 v16, 16, v52
	v_and_b32_e32 v17, 0xffff0000, v52
	v_pk_mul_f32 v[14:15], v[14:15], v[16:17]
	v_lshlrev_b32_e32 v16, 16, v53
	v_and_b32_e32 v17, 0xffff0000, v53
	v_pk_mul_f32 v[12:13], v[12:13], v[16:17]
	v_cvt_pk_bf16_f32 v14, v14, v15
	v_cvt_pk_bf16_f32 v15, v12, v13
	s_waitcnt vmcnt(6)
	v_lshlrev_b32_e32 v12, 16, v22
	v_and_b32_e32 v13, 0xffff0000, v22
	v_pk_mul_f32 v[8:9], v[8:9], v[12:13]
	v_lshlrev_b32_e32 v12, 16, v23
	v_and_b32_e32 v13, 0xffff0000, v23
	v_pk_mul_f32 v[10:11], v[10:11], v[12:13]
	v_cvt_pk_bf16_f32 v8, v8, v9
	v_cvt_pk_bf16_f32 v9, v10, v11
	global_store_dwordx2 v[36:37], v[8:9], off offset:1184
	v_pk_mul_f32 v[4:5], v[4:5], v[48:49] op_sel_hi:[1,0]
	s_waitcnt vmcnt(6)
	v_lshlrev_b32_e32 v8, 16, v42
	v_and_b32_e32 v9, 0xffff0000, v42
	v_pk_mul_f32 v[4:5], v[4:5], v[8:9]
	v_pk_mul_f32 v[6:7], v[6:7], v[48:49] op_sel_hi:[1,0]
	v_lshlrev_b32_e32 v8, 16, v43
	v_and_b32_e32 v9, 0xffff0000, v43
	v_pk_mul_f32 v[6:7], v[6:7], v[8:9]
	v_cvt_pk_bf16_f32 v4, v4, v5
	v_cvt_pk_bf16_f32 v5, v6, v7
	global_store_dwordx2 v[36:37], v[4:5], off offset:1216
	v_pk_mul_f32 v[0:1], v[0:1], v[48:49] op_sel_hi:[1,0]
	s_waitcnt vmcnt(6)
	v_lshlrev_b32_e32 v4, 16, v34
	v_and_b32_e32 v5, 0xffff0000, v34
	v_pk_mul_f32 v[0:1], v[0:1], v[4:5]
	v_pk_mul_f32 v[2:3], v[2:3], v[48:49] op_sel_hi:[1,0]
	v_lshlrev_b32_e32 v4, 16, v35
	v_and_b32_e32 v5, 0xffff0000, v35
	v_pk_mul_f32 v[2:3], v[2:3], v[4:5]
	v_cvt_pk_bf16_f32 v0, v0, v1
	v_cvt_pk_bf16_f32 v1, v2, v3
	global_store_dwordx2 v[36:37], v[14:15], off offset:1152
	global_store_dwordx2 v[36:37], v[0:1], off offset:1248
	s_barrier
	s_cbranch_scc1 .LBB0_623

.LBB0_655:
	v_lshlrev_b32_e32 v32, 3, v237
	v_or_b32_e32 v32, v32, v64
	v_mul_u32_u24_e32 v32, 0x110, v32
	v_add3_u32 v76, s20, v32, v65
	ds_read_b64_tr_b16 v[80:81], v76
	ds_read_b64_tr_b16 v[82:83], v76 offset:1088
	ds_read_b64_tr_b16 v[84:85], v76 offset:32
	ds_read_b64_tr_b16 v[86:87], v76 offset:1120
	ds_read_b64_tr_b16 v[88:89], v76 offset:64
	ds_read_b64_tr_b16 v[90:91], v76 offset:1152
	ds_read_b64_tr_b16 v[92:93], v76 offset:96
	ds_read_b64_tr_b16 v[94:95], v76 offset:1184
	s_waitcnt vmcnt(3) lgkmcnt(6)
	v_mfma_f32_16x16x32_bf16 v[56:59], v[80:83], v[204:207], 0
	ds_read_b64_tr_b16 v[80:81], v76 offset:128
	ds_read_b64_tr_b16 v[82:83], v76 offset:1216
	s_waitcnt lgkmcnt(6)
	v_mfma_f32_16x16x32_bf16 v[60:63], v[84:87], v[204:207], 0
	ds_read_b64_tr_b16 v[84:85], v76 offset:160
	ds_read_b64_tr_b16 v[86:87], v76 offset:1248
	s_waitcnt lgkmcnt(6)
	v_mfma_f32_16x16x32_bf16 v[44:47], v[88:91], v[204:207], 0
	ds_read_b64_tr_b16 v[88:89], v76 offset:192
	ds_read_b64_tr_b16 v[90:91], v76 offset:1280
	s_waitcnt lgkmcnt(6)
	v_mfma_f32_16x16x32_bf16 v[40:43], v[92:95], v[204:207], 0
	ds_read_b64_tr_b16 v[92:93], v76 offset:224
	ds_read_b64_tr_b16 v[94:95], v76 offset:1312
	s_waitcnt lgkmcnt(6)
	v_mfma_f32_16x16x32_bf16 v[48:51], v[80:83], v[204:207], 0
	ds_read_b64_tr_b16 v[80:81], v76 offset:8704
	ds_read_b64_tr_b16 v[82:83], v76 offset:9792
	s_waitcnt lgkmcnt(6)
	v_mfma_f32_16x16x32_bf16 v[36:39], v[84:87], v[204:207], 0
	ds_read_b64_tr_b16 v[84:85], v76 offset:8736
	ds_read_b64_tr_b16 v[86:87], v76 offset:9824
	s_waitcnt lgkmcnt(6)
	v_mfma_f32_16x16x32_bf16 v[32:35], v[88:91], v[204:207], 0
	ds_read_b64_tr_b16 v[88:89], v76 offset:8768
	ds_read_b64_tr_b16 v[90:91], v76 offset:9856
	s_waitcnt lgkmcnt(6)
	v_mfma_f32_16x16x32_bf16 v[52:55], v[92:95], v[204:207], 0
	ds_read_b64_tr_b16 v[92:93], v76 offset:8800
	ds_read_b64_tr_b16 v[94:95], v76 offset:9888
	s_waitcnt vmcnt(2) lgkmcnt(6)
	v_mfma_f32_16x16x32_bf16 v[56:59], v[80:83], v[200:203], v[56:59]
	ds_read_b64_tr_b16 v[80:81], v76 offset:8832
	ds_read_b64_tr_b16 v[82:83], v76 offset:9920
	s_waitcnt lgkmcnt(6)
	v_mfma_f32_16x16x32_bf16 v[60:63], v[84:87], v[200:203], v[60:63]
	ds_read_b64_tr_b16 v[84:85], v76 offset:8864
	ds_read_b64_tr_b16 v[86:87], v76 offset:9952
	s_waitcnt lgkmcnt(6)
	v_mfma_f32_16x16x32_bf16 v[44:47], v[88:91], v[200:203], v[44:47]
	ds_read_b64_tr_b16 v[88:89], v76 offset:8896
	ds_read_b64_tr_b16 v[90:91], v76 offset:9984
	s_waitcnt lgkmcnt(6)
	v_mfma_f32_16x16x32_bf16 v[40:43], v[92:95], v[200:203], v[40:43]
	ds_read_b64_tr_b16 v[92:93], v76 offset:8928
	ds_read_b64_tr_b16 v[94:95], v76 offset:10016
	s_waitcnt lgkmcnt(6)
	v_mfma_f32_16x16x32_bf16 v[48:51], v[80:83], v[200:203], v[48:51]
	ds_read_b64_tr_b16 v[80:81], v76 offset:17408
	ds_read_b64_tr_b16 v[82:83], v76 offset:18496
	s_waitcnt lgkmcnt(6)
	v_mfma_f32_16x16x32_bf16 v[36:39], v[84:87], v[200:203], v[36:39]
	ds_read_b64_tr_b16 v[84:85], v76 offset:17440
	ds_read_b64_tr_b16 v[86:87], v76 offset:18528
	s_waitcnt lgkmcnt(6)
	v_mfma_f32_16x16x32_bf16 v[32:35], v[88:91], v[200:203], v[32:35]
	ds_read_b64_tr_b16 v[88:89], v76 offset:17472
	ds_read_b64_tr_b16 v[90:91], v76 offset:18560
	s_waitcnt lgkmcnt(6)
	v_mfma_f32_16x16x32_bf16 v[52:55], v[92:95], v[200:203], v[52:55]
	ds_read_b64_tr_b16 v[92:93], v76 offset:17504
	ds_read_b64_tr_b16 v[94:95], v76 offset:18592
	s_waitcnt vmcnt(1) lgkmcnt(6)
	v_mfma_f32_16x16x32_bf16 v[56:59], v[80:83], v[196:199], v[56:59]
	ds_read_b64_tr_b16 v[80:81], v76 offset:17536
	ds_read_b64_tr_b16 v[82:83], v76 offset:18624
	s_waitcnt lgkmcnt(6)
	v_mfma_f32_16x16x32_bf16 v[60:63], v[84:87], v[196:199], v[60:63]
	ds_read_b64_tr_b16 v[84:85], v76 offset:17568
	ds_read_b64_tr_b16 v[86:87], v76 offset:18656
	s_waitcnt lgkmcnt(6)
	v_mfma_f32_16x16x32_bf16 v[44:47], v[88:91], v[196:199], v[44:47]
	ds_read_b64_tr_b16 v[88:89], v76 offset:17600
	ds_read_b64_tr_b16 v[90:91], v76 offset:18688
	s_waitcnt lgkmcnt(6)
	v_mfma_f32_16x16x32_bf16 v[40:43], v[92:95], v[196:199], v[40:43]
	ds_read_b64_tr_b16 v[92:93], v76 offset:17632
	ds_read_b64_tr_b16 v[94:95], v76 offset:18720
	s_waitcnt lgkmcnt(6)
	v_mfma_f32_16x16x32_bf16 v[48:51], v[80:83], v[196:199], v[48:51]
	ds_read_b64_tr_b16 v[80:81], v76 offset:26112
	ds_read_b64_tr_b16 v[82:83], v76 offset:27200
	s_waitcnt lgkmcnt(6)
	v_mfma_f32_16x16x32_bf16 v[36:39], v[84:87], v[196:199], v[36:39]
	ds_read_b64_tr_b16 v[84:85], v76 offset:26144
	ds_read_b64_tr_b16 v[86:87], v76 offset:27232
	s_waitcnt lgkmcnt(6)
	v_mfma_f32_16x16x32_bf16 v[32:35], v[88:91], v[196:199], v[32:35]
	ds_read_b64_tr_b16 v[88:89], v76 offset:26176
	ds_read_b64_tr_b16 v[90:91], v76 offset:27264
	s_waitcnt lgkmcnt(6)
	v_mfma_f32_16x16x32_bf16 v[52:55], v[92:95], v[196:199], v[52:55]
	ds_read_b64_tr_b16 v[92:93], v76 offset:26208
	ds_read_b64_tr_b16 v[94:95], v76 offset:27296
	s_waitcnt vmcnt(0) lgkmcnt(6)
	v_mfma_f32_16x16x32_bf16 v[56:59], v[80:83], v[192:195], v[56:59]
	ds_read_b64_tr_b16 v[80:81], v76 offset:26240
	ds_read_b64_tr_b16 v[82:83], v76 offset:27328
	s_waitcnt lgkmcnt(6)
	v_mfma_f32_16x16x32_bf16 v[60:63], v[84:87], v[192:195], v[60:63]
	ds_read_b64_tr_b16 v[84:85], v76 offset:26272
	ds_read_b64_tr_b16 v[86:87], v76 offset:27360
	s_waitcnt lgkmcnt(6)
	v_mfma_f32_16x16x32_bf16 v[44:47], v[88:91], v[192:195], v[44:47]
	ds_read_b64_tr_b16 v[88:89], v76 offset:26304
	ds_read_b64_tr_b16 v[90:91], v76 offset:27392
	s_waitcnt lgkmcnt(6)
	v_mfma_f32_16x16x32_bf16 v[40:43], v[92:95], v[192:195], v[40:43]
	ds_read_b64_tr_b16 v[92:93], v76 offset:26336
	ds_read_b64_tr_b16 v[94:95], v76 offset:27424
	s_waitcnt lgkmcnt(6)
	v_mfma_f32_16x16x32_bf16 v[48:51], v[80:83], v[192:195], v[48:51]
	s_waitcnt lgkmcnt(4)
	v_mfma_f32_16x16x32_bf16 v[36:39], v[84:87], v[192:195], v[36:39]
	s_waitcnt lgkmcnt(2)
	v_mfma_f32_16x16x32_bf16 v[32:35], v[88:91], v[192:195], v[32:35]
	s_waitcnt lgkmcnt(0)
	v_mfma_f32_16x16x32_bf16 v[52:55], v[92:95], v[192:195], v[52:55]
	s_branch .LBB0_627

.LBB0_804:
	s_barrier
	ds_write_b128 v181, v[64:67]
	ds_write_b128 v181, v[68:71] offset:64
	ds_write_b128 v181, v[72:75] offset:128
	ds_write_b128 v181, v[76:79] offset:192
	ds_write_b128 v181, v[80:83] offset:4352
	ds_write_b128 v181, v[84:87] offset:4416
	ds_write_b128 v181, v[88:91] offset:4480
	ds_write_b128 v181, v[92:95] offset:4544
	ds_write_b128 v181, v[96:99] offset:8704
	ds_write_b128 v181, v[100:103] offset:8768
	ds_write_b128 v181, v[104:107] offset:8832
	ds_write_b128 v181, v[108:111] offset:8896
	ds_write_b128 v181, v[112:115] offset:13056
	ds_write_b128 v181, v[116:119] offset:13120
	ds_write_b128 v181, v[120:123] offset:13184
	ds_write_b128 v181, v[124:127] offset:13248
	s_waitcnt lgkmcnt(0)
	s_barrier
	s_waitcnt vmcnt(6)
	ds_read_b128 v[4:7], v182
	v_add_u32_e32 v0, s7, v178
	v_ashrrev_i32_e32 v1, 31, v0
	v_lshl_add_u64 v[2:3], v[0:1], 2, s[76:77]
	global_load_dword v64, v[2:3], off
	v_lshlrev_b64 v[0:1], 13, v[0:1]
	s_waitcnt vmcnt(5) lgkmcnt(0)
	v_pk_add_f32 v[8:9], v[6:7], 0 op_sel_hi:[1,0]
	v_pk_add_f32 v[10:11], v[4:5], 0 op_sel_hi:[1,0]
	ds_read_b128 v[4:7], v182 offset:128
	v_lshl_add_u64 v[0:1], s[88:89], 0, v[0:1]
	s_ashr_i32 s7, s6, 31
	s_add_i32 s16, s16, s78
	s_cmpk_gt_i32 s16, 0xff
	s_waitcnt vmcnt(4) lgkmcnt(0)
	v_pk_add_f32 v[12:13], v[6:7], 0 op_sel_hi:[1,0]
	v_pk_add_f32 v[14:15], v[4:5], 0 op_sel_hi:[1,0]
	ds_read_b128 v[4:7], v182 offset:17408
	s_waitcnt lgkmcnt(0)
	v_pk_add_f32 v[8:9], v[8:9], v[6:7]
	v_pk_add_f32 v[10:11], v[10:11], v[4:5]
	ds_read_b128 v[4:7], v182 offset:17536
	s_waitcnt lgkmcnt(0)
	v_pk_add_f32 v[12:13], v[12:13], v[6:7]
	v_pk_add_f32 v[14:15], v[14:15], v[4:5]
	ds_read_b128 v[4:7], v182 offset:34816
	s_waitcnt lgkmcnt(0)
	v_pk_add_f32 v[8:9], v[8:9], v[6:7]
	v_pk_add_f32 v[10:11], v[10:11], v[4:5]
	ds_read_b128 v[4:7], v182 offset:34944
	s_waitcnt lgkmcnt(0)
	v_pk_add_f32 v[12:13], v[12:13], v[6:7]
	v_pk_add_f32 v[14:15], v[14:15], v[4:5]
	ds_read_b128 v[4:7], v183
	s_waitcnt lgkmcnt(0)
	v_pk_add_f32 v[8:9], v[8:9], v[6:7]
	v_pk_add_f32 v[10:11], v[10:11], v[4:5]
	ds_read_b128 v[4:7], v183 offset:128
	s_waitcnt lgkmcnt(0)
	v_pk_add_f32 v[6:7], v[12:13], v[6:7]
	v_pk_add_f32 v[4:5], v[14:15], v[4:5]
	s_waitcnt vmcnt(0)
	v_fmamk_f32 v12, v64, 0x3a800000, v228
	v_cmp_gt_f32_e32 vcc, s69, v12
	v_mul_f32_e32 v13, 0x4b800000, v12
	s_nop 0
	v_cndmask_b32_e32 v12, v12, v13, vcc
	v_rsq_f32_e32 v12, v12
	s_nop 0
	v_mul_f32_e32 v13, 0x45800000, v12
	v_cndmask_b32_e32 v12, v12, v13, vcc
	v_mul_f32_e32 v10, v10, v12
	v_mul_f32_e32 v4, v4, v12
	v_mul_f32_e32 v11, v11, v12
	v_mul_f32_e32 v5, v5, v12
	v_mul_f32_e32 v8, v8, v12
	v_mul_f32_e32 v6, v6, v12
	v_mul_f32_e32 v9, v9, v12
	v_mul_f32_e32 v7, v7, v12
	v_max_f32_e32 v10, 0, v10
	v_max_f32_e32 v4, 0, v4
	v_max_f32_e32 v11, 0, v11
	v_max_f32_e32 v5, 0, v5
	v_max_f32_e32 v8, 0, v8
	v_max_f32_e32 v6, 0, v6
	v_max_f32_e32 v9, 0, v9
	v_max_f32_e32 v7, 0, v7
	v_or_b32_e32 v12, s6, v164
	v_pk_mul_f32 v[10:11], v[10:11], v[10:11]
	v_pk_mul_f32 v[4:5], v[4:5], v[4:5]
	v_pk_mul_f32 v[8:9], v[8:9], v[8:9]
	v_pk_mul_f32 v[6:7], v[6:7], v[6:7]
	v_ashrrev_i32_e32 v13, 31, v12
	v_cvt_pk_bf16_f32 v10, v10, v11
	v_cvt_pk_bf16_f32 v11, v8, v9
	v_cvt_pk_bf16_f32 v4, v4, v5
	v_cvt_pk_bf16_f32 v5, v6, v7
	v_lshl_add_u64 v[6:7], v[12:13], 1, v[0:1]
	global_store_dwordx2 v[6:7], v[10:11], off
	global_store_dwordx2 v[6:7], v[4:5], off offset:64
	global_load_dword v2, v[2:3], off
	ds_read_b128 v[4:7], v182 offset:64
	s_waitcnt lgkmcnt(0)
	v_pk_add_f32 v[8:9], v[6:7], 0 op_sel_hi:[1,0]
	v_pk_add_f32 v[10:11], v[4:5], 0 op_sel_hi:[1,0]
	ds_read_b128 v[4:7], v182 offset:192
	s_waitcnt lgkmcnt(0)
	v_pk_add_f32 v[12:13], v[6:7], 0 op_sel_hi:[1,0]
	v_pk_add_f32 v[14:15], v[4:5], 0 op_sel_hi:[1,0]
	ds_read_b128 v[4:7], v182 offset:17472
	s_waitcnt lgkmcnt(0)
	v_pk_add_f32 v[8:9], v[8:9], v[6:7]
	v_pk_add_f32 v[10:11], v[10:11], v[4:5]
	ds_read_b128 v[4:7], v182 offset:17600
	s_waitcnt lgkmcnt(0)
	v_pk_add_f32 v[12:13], v[12:13], v[6:7]
	v_pk_add_f32 v[14:15], v[14:15], v[4:5]
	ds_read_b128 v[4:7], v182 offset:34880
	s_waitcnt lgkmcnt(0)
	v_pk_add_f32 v[16:17], v[8:9], v[6:7]
	v_pk_add_f32 v[10:11], v[10:11], v[4:5]
	ds_read_b128 v[4:7], v182 offset:35008
	s_waitcnt lgkmcnt(0)
	v_pk_add_f32 v[18:19], v[12:13], v[6:7]
	ds_read_b128 v[6:9], v183 offset:64
	v_pk_add_f32 v[14:15], v[14:15], v[4:5]
	s_waitcnt lgkmcnt(0)
	v_pk_add_f32 v[4:5], v[16:17], v[8:9]
	v_pk_add_f32 v[8:9], v[10:11], v[6:7]
	ds_read_b128 v[10:13], v183 offset:192
	s_waitcnt lgkmcnt(0)
	v_pk_add_f32 v[6:7], v[18:19], v[12:13]
	v_pk_add_f32 v[10:11], v[14:15], v[10:11]
	s_waitcnt vmcnt(0)
	v_fmamk_f32 v2, v2, 0x3a800000, v228
	v_cmp_gt_f32_e32 vcc, s69, v2
	v_mul_f32_e32 v3, 0x4b800000, v2
	s_nop 0
	v_cndmask_b32_e32 v2, v2, v3, vcc
	v_rsq_f32_e32 v2, v2
	s_nop 0
	v_mul_f32_e32 v3, 0x45800000, v2
	v_cndmask_b32_e32 v12, v2, v3, vcc
	v_mul_f32_e32 v3, v10, v12
	v_mul_f32_e32 v2, v8, v12
	v_max_f32_e32 v8, 0, v3
	v_mul_f32_e32 v3, v9, v12
	v_mul_f32_e32 v4, v4, v12
	v_mul_f32_e32 v6, v6, v12
	v_mul_f32_e32 v5, v5, v12
	v_mul_f32_e32 v7, v7, v12
	v_max_f32_e32 v2, 0, v2
	v_max_f32_e32 v3, 0, v3
	v_max_f32_e32 v4, 0, v4
	v_max_f32_e32 v6, 0, v6
	v_max_f32_e32 v5, 0, v5
	v_max_f32_e32 v7, 0, v7
	v_mul_f32_e32 v9, v11, v12
	v_pk_mul_f32 v[2:3], v[2:3], v[2:3]
	v_pk_mul_f32 v[4:5], v[4:5], v[4:5]
	v_pk_mul_f32 v[6:7], v[6:7], v[6:7]
	v_max_f32_e32 v9, 0, v9
	v_cvt_pk_bf16_f32 v2, v2, v3
	v_cvt_pk_bf16_f32 v3, v4, v5
	v_cvt_pk_bf16_f32 v5, v6, v7
	v_lshl_add_u64 v[6:7], s[6:7], 0, v[164:165]
	v_pk_mul_f32 v[8:9], v[8:9], v[8:9]
	v_lshl_add_u64 v[0:1], v[6:7], 1, v[0:1]
	v_cvt_pk_bf16_f32 v4, v8, v9
	global_store_dwordx2 v[0:1], v[2:3], off offset:32
	global_store_dwordx2 v[0:1], v[4:5], off offset:96
	s_barrier
	s_cbranch_scc1 .LBB0_811
